# W2 (MLP down) processes its second unit round first: reads the Hb rows the W1 phase wrote last (MALL reuse); on top of ResAdd x_old prefetch
# speedup vs baseline: 1.0020x; 1.0020x over previous
.LBB0_2382:
	v_readlane_b32 s0, v255, 29
	s_or_b32 s2, s0, 11
	v_readlane_b32 s4, v253, 2
	v_readlane_b32 s5, v253, 3
	s_cmp_le_i32 s4, s2
	s_cselect_b64 s[0:1], -1, 0
	s_cmp_lt_i32 s2, s5
	s_cselect_b64 s[2:3], -1, 0
	s_and_b64 s[0:1], s[0:1], s[2:3]
	s_andn2_b64 vcc, exec, s[0:1]
	v_readlane_b32 s6, v253, 4
	v_readlane_b32 s7, v253, 5
	s_cbranch_vccnz .LBB0_2486
	s_mov_b32 s0, -1
	s_mov_b32 s4, s85
	s_waitcnt vmcnt(0)
	v_mbcnt_lo_u32_b32 v0, s0, 0
	v_mbcnt_hi_u32_b32 v146, s0, v0
	s_mov_b32 s5, s97
	s_cmpk_lt_i32 s5, 0x200
	v_add_u32_e32 v145, s90, v146
	s_mov_b64 s[0:1], s[48:49]
	v_readfirstlane_b32 s33, v145
	s_movk_i32 s26, 0x1000
	s_waitcnt lgkmcnt(0)
	s_cselect_b64 s[14:15], -1, 0
	s_cmpk_gt_i32 s5, 0x1ff
	s_cbranch_scc1 .LBB0_2389
	s_add_i32 s3, s5, 0x100
	s_ashr_i32 s2, s3, 31
	s_lshr_b32 s2, s2, 29
	s_add_i32 s6, s3, s2
	s_and_b32 s2, s6, -8
	s_sub_i32 s7, s3, s2
	s_cmp_gt_i32 s7, -1
	s_mov_b64 s[2:3], -1
	s_cbranch_scc0 .LBB0_2386
	s_lshl_b32 s10, s7, 6
	s_mov_b64 s[2:3], 0

.LBB0_2395:
	s_add_i32 s57, s57, 1
	s_mul_i32 s33, s57, s58
	s_mul_hi_u32 s40, s57, s4
	s_add_i32 s33, s40, s33
	s_mul_i32 s40, s57, s4
	s_add_u32 s40, s40, s5
	s_addc_u32 s41, s33, s59
	v_cmp_gt_i64_e32 vcc, s[40:41], v[236:237]
	v_cmp_lt_i64_e64 s[42:43], s[40:41], v[234:235]
	s_cbranch_vccnz .LBB0_2401
	s_lshl_b32 s33, s5, 1
	s_addk_i32 s33, 0x100
	s_sub_i32 s40, s33, s40
	s_ashr_i32 s33, s40, 31
	s_lshr_b32 s33, s33, 29
	s_add_i32 s33, s40, s33
	s_and_b32 s41, s33, -8
	s_sub_i32 s44, s40, s41
	s_cmp_gt_i32 s44, -1
	s_mov_b64 s[40:41], -1
	s_cbranch_scc0 .LBB0_2398
	s_lshl_b32 s45, s44, 6
	s_mov_b64 s[40:41], 0
